# flat->global K/V prefetch loads in attention, softmax cross-lane reductions via v_permlane16/32_swap instead of ds_bpermute, removed remaining prologue vmcnt(0) drains in gemm256
# speedup vs baseline: 1.0563x; 1.0103x over previous
; #define STAGE(P, BASE, LD, br, kt) do { const long _g = (long)(br) * (LD) + (long)(kt) * 64; \
;     _Pragma("unroll") for (int _i = 0; _i < 2; ++_i) { const int _b = tid * 16 + _i * 8192; int _r, _c; stage_rc(_b, _r, _c); \
;       __builtin_amdgcn_global_load_lds((const G_AS1 unsigned*)((BASE) + _g + (long)_r * (LD) + _c), \
;         (LAS unsigned*)((char*)(P) + _b), 16, 0, 0); } } while (0)
; #define BAR __builtin_amdgcn_s_barrier()
; __device__ __forceinline__ void gemm256(const bf16_t* __restrict__ A, long lda, const bf16_t* __restrict__ Bt, long ldb, int K,
;                                         int brow, int bcol, char* smem, f32x4 (&acc)[2][2][4][2]) {
;     ...
;     const int wid = tid >> 6, lane = tid & 63, wr = wid >> 2, wc = wid & 3, fr = lane & 15, fq = lane >> 4;
; #pragma unroll
;     for (int ai = 0; ai < 2; ++ai)
; #pragma unroll
;         for (int bj = 0; bj < 2; ++bj)
; #pragma unroll
;             for (int m = 0; m < 4; ++m)
; #pragma unroll
;                 for (int n = 0; n < 2; ++n) acc[ai][bj][m][n] = (f32x4){0.f, 0.f, 0.f, 0.f};
;     bf16x8 At[4][2], B0[2][2], B1[2][2];
;     const int nt = K / 64;
;     __syncthreads();
;     STAGE(SB(0, 0), Bt, ldb, bcol, 0); STAGE(SA(0, 0), A, lda, brow, 0);
;     STAGE(SB(0, 1), Bt, ldb, bcol + 128, 0); STAGE(SA(0, 1), A, lda, brow + 128, 0);
;     if (wr == 1) BAR;
.LBB0_362:
	s_ashr_i32 s10, s25, 31
	s_lshr_b32 s10, s10, 29
	s_add_i32 s10, s25, s10
	s_ashr_i32 s11, s10, 3
	s_and_b32 s10, s10, -8
	s_sub_i32 s10, s25, s10
	s_cmp_lt_i32 s10, 0
	s_movk_i32 s16, 0x16c
	s_cselect_b32 s16, s16, 0x16b
	v_mov_b32_e32 v0, v236
	s_mul_i32 s10, s10, s16
	s_add_i32 s10, s10, s11
	v_ashrrev_i32_e32 v2, 31, v0
	v_lshrrev_b32_e32 v2, 26, v2
	s_mul_hi_i32 s11, s10, 0x2e8ba2e9
	v_add_u32_e32 v2, v0, v2
	s_lshr_b32 s16, s11, 31
	s_ashr_i32 s11, s11, 4
	v_ashrrev_i32_e32 v3, 6, v2
	v_bfe_i32 v2, v0, 27, 1
	s_add_i32 s11, s11, s16
	v_lshlrev_b32_e32 v5, 4, v0
	v_lshrrev_b32_e32 v2, 22, v2
	s_mul_i32 s16, s11, 0x58
	v_add_u32_e32 v2, v5, v2
	s_sub_i32 s10, s10, s16
	v_and_b32_e32 v2, 0xfffffc00, v2
	s_bfe_i32 s16, s10, 0x80000
	v_sub_u32_e32 v2, v5, v2
	s_bfe_u32 s16, s16, 0x2000d
	v_lshrrev_b32_e32 v6, 4, v2
	s_add_i32 s16, s10, s16
	v_bitop3_b32 v6, v6, v2, 32 bitop3:0x6c
	v_ashrrev_i32_e32 v2, 31, v2
	s_bfe_i32 s17, s16, 0x80000
	v_lshrrev_b32_e32 v2, 26, v2
	s_sext_i32_i16 s17, s17
	s_and_b32 s16, s16, 0xfc
	v_lshlrev_b32_e32 v7, 3, v3
	v_add_u32_e32 v2, v6, v2
	s_sub_i32 s10, s10, s16
	s_ashr_i32 s26, s17, 2
	v_and_b32_e32 v7, -16, v7
	v_ashrrev_i32_e32 v8, 6, v2
	s_sext_i32_i8 s10, s10
	s_lshl_b32 s20, s26, 8
	v_add_u32_e32 v2, v8, v7
	v_mul_i32_i24_e32 v7, 64, v8
	s_lshl_b32 s11, s11, 10
	s_lshl_b32 s10, s10, 8
	s_ashr_i32 s21, s20, 31
	v_lshlrev_b32_e32 v3, 5, v3
	v_sub_u32_e32 v6, v6, v7
	s_add_i32 s10, s10, s11
	s_lshl_b64 s[16:17], s[20:21], 11
	v_and_b32_e32 v3, 32, v3
	v_ashrrev_i16_sdwa v6, v240, sext(v6) dst_sel:DWORD dst_unused:UNUSED_PAD src0_sel:DWORD src1_sel:BYTE_0
	s_add_u32 s18, s7, s16
	v_add_u32_sdwa v8, v3, sext(v6) dst_sel:DWORD dst_unused:UNUSED_PAD src0_sel:DWORD src1_sel:WORD_0
	v_ashrrev_i32_e32 v3, 31, v2
	s_addc_u32 s19, s24, s17
	v_lshlrev_b64 v[6:7], 11, v[2:3]
	v_ashrrev_i32_e32 v9, 31, v8
	v_lshl_add_u64 v[2:3], s[18:19], 0, v[6:7]
	v_lshlrev_b64 v[8:9], 1, v[8:9]
	v_add_u32_e32 v145, 0x2000, v5
	v_lshl_add_u64 v[14:15], v[2:3], 0, v[8:9]
	v_ashrrev_i32_e32 v2, 31, v145
	v_lshrrev_b32_e32 v2, 22, v2
	v_add_u32_e32 v2, v145, v2
	v_ashrrev_i32_e32 v3, 10, v2
	v_mul_i32_i24_e32 v2, 0x400, v3
	v_sub_u32_e32 v2, v145, v2
	v_lshrrev_b32_e32 v10, 4, v2
	v_bitop3_b32 v10, v10, v2, 32 bitop3:0x6c
	v_ashrrev_i32_e32 v11, 31, v10
	v_lshrrev_b32_e32 v11, 26, v11
	v_add_u32_e32 v11, v10, v11
	v_lshlrev_b32_e32 v2, 3, v3
	v_ashrrev_i32_e32 v12, 6, v11
	v_and_b32_e32 v11, 0xc0, v11
	v_add_u32_e32 v144, 0x10000, v5
	v_and_b32_e32 v2, -16, v2
	v_lshlrev_b32_e32 v3, 5, v3
	v_sub_u32_e32 v10, v10, v11
	v_readfirstlane_b32 s11, v144
	v_add_u32_e32 v2, v12, v2
	v_and_b32_e32 v3, 32, v3
	v_ashrrev_i16_sdwa v10, v240, sext(v10) dst_sel:DWORD dst_unused:UNUSED_PAD src0_sel:DWORD src1_sel:BYTE_0
	v_add_u32_e32 v150, 0x12000, v5
	s_mov_b32 m0, s11
	v_add_u32_sdwa v12, v3, sext(v10) dst_sel:DWORD dst_unused:UNUSED_PAD src0_sel:DWORD src1_sel:WORD_0
	v_ashrrev_i32_e32 v3, 31, v2
	v_readfirstlane_b32 s11, v150
	s_barrier
	global_load_lds_dwordx4 v[14:15], off
	v_lshlrev_b64 v[10:11], 11, v[2:3]
	s_mov_b32 m0, s11
	s_ashr_i32 s11, s10, 31
	v_lshl_add_u64 v[2:3], s[18:19], 0, v[10:11]
	s_lshl_b64 s[18:19], s[10:11], 11
	s_add_u32 s28, s22, s18
	s_addc_u32 s29, s23, s19
	s_bitset1_b32 s20, 7
	v_ashrrev_i32_e32 v13, 31, v12
	s_ashr_i32 s21, s20, 31
	v_lshlrev_b64 v[12:13], 1, v[12:13]
	s_lshl_b64 s[20:21], s[20:21], 11
	v_lshl_add_u64 v[16:17], v[2:3], 0, v[12:13]
	v_lshl_add_u64 v[2:3], s[28:29], 0, v[6:7]
	s_add_u32 s20, s7, s20
	v_lshl_add_u64 v[18:19], v[2:3], 0, v[8:9]
	v_lshl_add_u64 v[2:3], s[28:29], 0, v[10:11]
	s_addc_u32 s21, s24, s21
	v_lshl_add_u64 v[20:21], v[2:3], 0, v[12:13]
	v_lshl_add_u64 v[2:3], s[20:21], 0, v[6:7]
	v_lshl_add_u64 v[22:23], v[2:3], 0, v[8:9]
	v_lshl_add_u64 v[2:3], s[20:21], 0, v[10:11]
	s_or_b32 s20, s10, 0x80
	v_readfirstlane_b32 s11, v5
	s_ashr_i32 s21, s20, 31
	global_load_lds_dwordx4 v[16:17], off
	s_mov_b32 m0, s11
	v_readfirstlane_b32 s11, v145
	v_add_u32_e32 v152, 0x14000, v5
	s_lshl_b64 s[20:21], s[20:21], 11
	global_load_lds_dwordx4 v[18:19], off
	s_mov_b32 m0, s11
	v_readfirstlane_b32 s11, v152
	v_add_u32_e32 v154, 0x16000, v5
	s_add_u32 s20, s22, s20
	global_load_lds_dwordx4 v[20:21], off
	s_mov_b32 m0, s11
	v_readfirstlane_b32 s11, v154
	s_addc_u32 s21, s23, s21
	v_add_u32_e32 v155, 0x4000, v5
	global_load_lds_dwordx4 v[22:23], off
	s_nop 0
	v_lshl_add_u64 v[24:25], v[2:3], 0, v[12:13]
	s_mov_b32 m0, s11
	v_lshl_add_u64 v[2:3], s[20:21], 0, v[6:7]
	v_readfirstlane_b32 s11, v155
	v_add_u32_e32 v156, 0x6000, v5
	global_load_lds_dwordx4 v[24:25], off
	v_lshl_add_u64 v[2:3], v[2:3], 0, v[8:9]
	s_mov_b32 m0, s11
	v_lshl_add_u64 v[26:27], s[20:21], 0, v[10:11]
	v_readfirstlane_b32 s11, v156
	global_load_lds_dwordx4 v[2:3], off
	v_lshl_add_u64 v[134:135], v[26:27], 0, v[12:13]
	s_mov_b32 m0, s11
	v_ashrrev_i32_e32 v26, 8, v0
	global_load_lds_dwordx4 v[134:135], off
	v_cmp_eq_u32_e32 vcc, 1, v26
	s_and_saveexec_b64 s[20:21], vcc
	s_cbranch_execz .LBB0_364
	s_barrier

; #define STAGE(P, BASE, LD, br, kt) do { const long _g = (long)(br) * (LD) + (long)(kt) * 64; \
;     _Pragma("unroll") for (int _i = 0; _i < 2; ++_i) { const int _b = tid * 16 + _i * 8192; int _r, _c; stage_rc(_b, _r, _c); \
;       __builtin_amdgcn_global_load_lds((const G_AS1 unsigned*)((BASE) + _g + (long)_r * (LD) + _c), \
;         (LAS unsigned*)((char*)(P) + _b), 16, 0, 0); } } while (0)
; #define BAR __builtin_amdgcn_s_barrier()
; __device__ __forceinline__ void gemm256(const bf16_t* __restrict__ A, long lda, const bf16_t* __restrict__ Bt, long ldb, int K,
;                                         int brow, int bcol, char* smem, f32x4 (&acc)[2][2][4][2]) {
;     ...
;     const int wid = tid >> 6, lane = tid & 63, wr = wid >> 2, wc = wid & 3, fr = lane & 15, fq = lane >> 4;
; #pragma unroll
;     for (int ai = 0; ai < 2; ++ai)
; #pragma unroll
;         for (int bj = 0; bj < 2; ++bj)
; #pragma unroll
;             for (int m = 0; m < 4; ++m)
; #pragma unroll
;                 for (int n = 0; n < 2; ++n) acc[ai][bj][m][n] = (f32x4){0.f, 0.f, 0.f, 0.f};
;     bf16x8 At[4][2], B0[2][2], B1[2][2];
;     const int nt = K / 64;
;     __syncthreads();
;     STAGE(SB(0, 0), Bt, ldb, bcol, 0); STAGE(SA(0, 0), A, lda, brow, 0);
;     STAGE(SB(0, 1), Bt, ldb, bcol + 128, 0); STAGE(SA(0, 1), A, lda, brow + 128, 0);
;     if (wr == 1) BAR;
.LBB0_415:
	s_and_b64 vcc, exec, s[16:17]
	s_cbranch_vccz .LBB0_408
	s_ashr_i32 s16, s34, 31
	s_lshr_b32 s16, s16, 29
	s_add_i32 s16, s34, s16
	s_ashr_i32 s17, s16, 3
	s_and_b32 s16, s16, -8
	s_sub_i32 s16, s34, s16
	s_cmp_lt_i32 s16, 0
	s_movk_i32 s18, 0x43
	s_cselect_b32 s18, s18, 0x42
	s_mul_i32 s16, s16, s18
	s_add_i32 s16, s16, s17
	s_ashr_i32 s17, s16, 31
	v_mov_b32_e32 v0, v236
	s_lshr_b32 s17, s17, 28
	s_add_i32 s17, s16, s17
	v_bfe_i32 v3, v0, 27, 1
	v_lshlrev_b32_e32 v5, 4, v0
	v_lshrrev_b32_e32 v3, 22, v3
	s_and_b32 s18, s17, 0xfff0
	v_add_u32_e32 v3, v5, v3
	s_sub_i32 s16, s16, s18
	v_and_b32_e32 v3, 0xfffffc00, v3
	s_bfe_i32 s18, s16, 0x80000
	v_ashrrev_i32_e32 v2, 31, v0
	v_sub_u32_e32 v3, v5, v3
	s_bfe_u32 s18, s18, 0x2000d
	v_lshrrev_b32_e32 v2, 26, v2
	v_lshrrev_b32_e32 v6, 4, v3
	s_add_i32 s18, s16, s18
	v_add_u32_e32 v2, v0, v2
	v_bitop3_b32 v6, v6, v3, 32 bitop3:0x6c
	v_ashrrev_i32_e32 v3, 31, v3
	s_bfe_i32 s19, s18, 0x80000
	s_and_b32 s18, s18, 0xfc
	v_ashrrev_i32_e32 v2, 6, v2
	v_lshrrev_b32_e32 v3, 26, v3
	s_sext_i32_i16 s19, s19
	s_sub_i32 s16, s16, s18
	v_lshlrev_b32_e32 v7, 3, v2
	v_add_u32_e32 v3, v6, v3
	s_sext_i32_i8 s16, s16
	s_ashr_i32 s46, s19, 2
	s_lshl_b32 s17, s17, 6
	v_and_b32_e32 v7, -16, v7
	v_ashrrev_i32_e32 v3, 6, v3
	s_and_b32 s17, s17, 0xfffffc00
	s_lshl_b32 s35, s16, 8
	s_mul_i32 s16, s46, 0xb0000
	v_add_u32_e32 v18, v3, v7
	v_mul_i32_i24_e32 v3, 64, v3
	s_add_i32 s35, s35, s17
	s_ashr_i32 s17, s16, 31
	v_lshlrev_b32_e32 v2, 5, v2
	v_sub_u32_e32 v3, v6, v3
	s_lshl_b64 s[18:19], s[16:17], 1
	v_and_b32_e32 v2, 32, v2
	v_ashrrev_i16_sdwa v3, v240, sext(v3) dst_sel:DWORD dst_unused:UNUSED_PAD src0_sel:DWORD src1_sel:BYTE_0
	s_movk_i32 s22, 0xb00
	s_add_u32 s20, s28, s18
	v_add_u32_sdwa v2, v2, sext(v3) dst_sel:DWORD dst_unused:UNUSED_PAD src0_sel:DWORD src1_sel:WORD_0
	v_mad_i64_i32 v[134:135], s[16:17], v18, s22, 0
	s_addc_u32 s21, s29, s19
	v_lshlrev_b64 v[20:21], 1, v[134:135]
	v_ashrrev_i32_e32 v3, 31, v2
	v_lshl_add_u64 v[8:9], s[20:21], 0, v[20:21]
	v_lshlrev_b64 v[6:7], 1, v[2:3]
	v_add_u32_e32 v152, 0x2000, v5
	v_lshl_add_u64 v[10:11], v[8:9], 0, v[6:7]
	v_ashrrev_i32_e32 v8, 31, v152
	v_lshrrev_b32_e32 v8, 22, v8
	v_add_u32_e32 v8, v152, v8
	v_ashrrev_i32_e32 v8, 10, v8
	v_mul_i32_i24_e32 v9, 0x400, v8
	v_sub_u32_e32 v9, v152, v9
	v_lshrrev_b32_e32 v12, 4, v9
	v_bitop3_b32 v9, v12, v9, 32 bitop3:0x6c
	v_ashrrev_i32_e32 v13, 31, v9
	v_lshrrev_b32_e32 v13, 26, v13
	v_lshlrev_b32_e32 v12, 3, v8
	v_add_u32_e32 v13, v9, v13
	v_and_b32_e32 v12, -16, v12
	v_ashrrev_i32_e32 v14, 6, v13
	v_add_u32_e32 v148, 0x10000, v5
	v_add_u32_e32 v19, v14, v12
	v_and_b32_e32 v12, 0xc0, v13
	v_readfirstlane_b32 s16, v148
	v_lshlrev_b32_e32 v8, 5, v8
	v_sub_u32_e32 v9, v9, v12
	s_mov_b32 m0, s16
	v_and_b32_e32 v8, 32, v8
	v_ashrrev_i16_sdwa v9, v240, sext(v9) dst_sel:DWORD dst_unused:UNUSED_PAD src0_sel:DWORD src1_sel:BYTE_0
	v_mad_i64_i32 v[138:139], s[16:17], v19, s22, 0
	v_add_u32_e32 v155, 0x12000, v5
	v_add_u32_sdwa v136, v8, sext(v9) dst_sel:DWORD dst_unused:UNUSED_PAD src0_sel:DWORD src1_sel:WORD_0
	v_readfirstlane_b32 s16, v155
	s_mul_i32 s22, s35, 0x1600
	s_waitcnt vmcnt(63) expcnt(7) lgkmcnt(15)
	s_barrier
	global_load_lds_dwordx4 v[10:11], off
	v_lshlrev_b64 v[22:23], 1, v[138:139]
	v_ashrrev_i32_e32 v137, 31, v136
	s_mov_b32 m0, s16
	s_mul_hi_i32 s23, s35, 0x1600
	s_add_u32 s16, s7, s22
	v_lshl_add_u64 v[12:13], s[20:21], 0, v[22:23]
	v_lshlrev_b64 v[8:9], 1, v[136:137]
	s_addc_u32 s17, s26, s23
	v_lshl_add_u64 v[12:13], v[12:13], 0, v[8:9]
	v_lshl_add_u64 v[14:15], s[16:17], 0, v[20:21]
	v_readfirstlane_b32 s24, v5
	global_load_lds_dwordx4 v[12:13], off
	v_lshl_add_u64 v[14:15], v[14:15], 0, v[6:7]
	s_mov_b32 m0, s24
	v_lshl_add_u64 v[16:17], s[16:17], 0, v[22:23]
	v_readfirstlane_b32 s16, v152
	global_load_lds_dwordx4 v[14:15], off
	s_mov_b32 m0, s16
	s_add_u32 s16, s20, 0xb0000
	s_addc_u32 s17, s21, 0
	v_add_u32_e32 v156, 0x14000, v5
	v_lshl_add_u64 v[16:17], v[16:17], 0, v[8:9]
	s_nop 0
	v_lshl_add_u64 v[24:25], s[16:17], 0, v[20:21]
	v_readfirstlane_b32 s24, v156
	global_load_lds_dwordx4 v[16:17], off
	v_lshl_add_u64 v[24:25], v[24:25], 0, v[6:7]
	s_mov_b32 m0, s24
	v_add_u32_e32 v158, 0x16000, v5
	global_load_lds_dwordx4 v[24:25], off
	v_lshl_add_u64 v[24:25], s[16:17], 0, v[22:23]
	v_readfirstlane_b32 s16, v158
	s_mov_b32 m0, s16
	s_or_b32 s16, s35, 0x80
	s_mul_hi_i32 s17, s16, 0x1600
	s_mulk_i32 s16, 0x1600
	s_add_u32 s16, s7, s16
	s_addc_u32 s17, s26, s17
	v_add_u32_e32 v159, 0x4000, v5
	v_lshl_add_u64 v[24:25], v[24:25], 0, v[8:9]
	v_lshl_add_u64 v[20:21], s[16:17], 0, v[20:21]
	v_readfirstlane_b32 s24, v159
	global_load_lds_dwordx4 v[24:25], off
	v_lshl_add_u64 v[20:21], v[20:21], 0, v[6:7]
	s_mov_b32 m0, s24
	v_add_u32_e32 v160, 0x6000, v5
	global_load_lds_dwordx4 v[20:21], off
	v_lshl_add_u64 v[20:21], s[16:17], 0, v[22:23]
	v_readfirstlane_b32 s24, v160
	v_lshl_add_u64 v[20:21], v[20:21], 0, v[8:9]
	s_mov_b32 m0, s24
	s_nop 0
	global_load_lds_dwordx4 v[20:21], off
	v_ashrrev_i32_e32 v20, 8, v0
	v_cmp_eq_u32_e32 vcc, 1, v20
	s_and_saveexec_b64 s[24:25], vcc
	s_cbranch_execz .LBB0_418
	s_barrier

.LBB0_959:
	s_waitcnt vmcnt(0)
	global_load_dwordx4 v[24:27], v[202:203], off
	global_load_dwordx4 v[28:31], v[204:205], off
	global_load_dwordx4 v[32:35], v[206:207], off
	global_load_dwordx4 v[36:39], v[208:209], off
	s_mov_b64 s[12:13], 0x10000
	v_lshl_add_u64 v[202:203], v[202:203], 0, s[12:13]
	v_lshl_add_u64 v[204:205], v[204:205], 0, s[12:13]
	v_lshl_add_u64 v[206:207], v[206:207], 0, s[44:45]
	v_lshl_add_u64 v[208:209], v[208:209], 0, s[44:45]
	v_cmp_lt_i32_e32 vcc, 0, v211
	s_and_saveexec_b64 s[12:13], vcc
	s_cbranch_execz .LBB0_979

; #define STAGE(P, BASE, LD, br, kt) do { const long _g = (long)(br) * (LD) + (long)(kt) * 64; \
;     _Pragma("unroll") for (int _i = 0; _i < 2; ++_i) { const int _b = tid * 16 + _i * 8192; int _r, _c; stage_rc(_b, _r, _c); \
;       __builtin_amdgcn_global_load_lds((const G_AS1 unsigned*)((BASE) + _g + (long)_r * (LD) + _c), \
;         (LAS unsigned*)((char*)(P) + _b), 16, 0, 0); } } while (0)
; #define BAR __builtin_amdgcn_s_barrier()
; __device__ __forceinline__ void gemm256(const bf16_t* __restrict__ A, long lda, const bf16_t* __restrict__ Bt, long ldb, int K,
;                                         int brow, int bcol, char* smem, f32x4 (&acc)[2][2][4][2]) {
;     ...
;     const int wid = tid >> 6, lane = tid & 63, wr = wid >> 2, wc = wid & 3, fr = lane & 15, fq = lane >> 4;
; #pragma unroll
;     for (int ai = 0; ai < 2; ++ai)
; #pragma unroll
;         for (int bj = 0; bj < 2; ++bj)
; #pragma unroll
;             for (int m = 0; m < 4; ++m)
; #pragma unroll
;                 for (int n = 0; n < 2; ++n) acc[ai][bj][m][n] = (f32x4){0.f, 0.f, 0.f, 0.f};
;     bf16x8 At[4][2], B0[2][2], B1[2][2];
;     const int nt = K / 64;
;     __syncthreads();
;     STAGE(SB(0, 0), Bt, ldb, bcol, 0); STAGE(SA(0, 0), A, lda, brow, 0);
;     STAGE(SB(0, 1), Bt, ldb, bcol + 128, 0); STAGE(SA(0, 1), A, lda, brow + 128, 0);
;     if (wr == 1) BAR;
.LBB0_1030:
	s_and_b64 vcc, exec, s[6:7]
	s_cbranch_vccz .LBB0_1023
	s_ashr_i32 s6, s1, 31
	s_lshr_b32 s6, s6, 29
	s_add_i32 s6, s1, s6
	s_ashr_i32 s7, s6, 3
	s_and_b32 s6, s6, -8
	s_sub_i32 s6, s1, s6
	s_cmp_lt_i32 s6, 0
	s_movk_i32 s8, 0x43
	s_cselect_b32 s8, s8, 0x42
	s_mul_i32 s6, s6, s8
	s_add_i32 s6, s6, s7
	s_ashr_i32 s7, s6, 31
	s_lshr_b32 s7, s7, 28
	s_add_i32 s8, s6, s7
	s_and_b32 s7, s8, 0xfff0
	s_sub_i32 s9, s6, s7
	s_bfe_i32 s6, s9, 0x80000
	s_bfe_u32 s6, s6, 0x2000d
	v_mov_b32_e32 v0, v236
	s_add_i32 s10, s9, s6
	s_load_dwordx2 s[6:7], s[4:5], 0x130
	s_bfe_i32 s11, s10, 0x80000
	v_ashrrev_i32_e32 v2, 31, v0
	v_lshrrev_b32_e32 v2, 26, v2
	v_add_u32_e32 v2, v0, v2
	v_ashrrev_i32_e32 v3, 6, v2
	v_bfe_i32 v2, v0, 27, 1
	v_lshlrev_b32_e32 v5, 4, v0
	v_lshrrev_b32_e32 v2, 22, v2
	s_and_b32 s10, s10, 0xfc
	v_add_u32_e32 v2, v5, v2
	s_sub_i32 s9, s9, s10
	v_and_b32_e32 v2, 0xfffffc00, v2
	s_waitcnt lgkmcnt(0)
	s_add_u32 s18, s6, 0x346c000
	v_sub_u32_e32 v2, v5, v2
	s_addc_u32 s19, s7, 0
	v_lshrrev_b32_e32 v6, 4, v2
	s_add_u32 s20, s6, 0x326c000
	v_bitop3_b32 v6, v6, v2, 32 bitop3:0x6c
	v_ashrrev_i32_e32 v2, 31, v2
	s_sext_i32_i8 s9, s9
	s_addc_u32 s21, s7, 0
	s_lshl_b32 s8, s8, 6
	v_lshrrev_b32_e32 v2, 26, v2
	s_sext_i32_i16 s11, s11
	s_and_b32 s8, s8, 0xfffffc00
	s_lshl_b32 s9, s9, 8
	v_lshlrev_b32_e32 v7, 3, v3
	v_add_u32_e32 v2, v6, v2
	s_add_i32 s10, s9, s8
	s_lshl_b32 s8, s11, 6
	v_and_b32_e32 v7, -16, v7
	v_ashrrev_i32_e32 v8, 6, v2
	s_and_b32 s8, s8, 0xffffff00
	v_add_u32_e32 v2, v8, v7
	v_mul_i32_i24_e32 v7, 64, v8
	s_ashr_i32 s9, s8, 31
	v_lshlrev_b32_e32 v3, 5, v3
	v_sub_u32_e32 v6, v6, v7
	s_lshl_b64 s[12:13], s[8:9], 11
	v_and_b32_e32 v3, 32, v3
	v_ashrrev_i16_sdwa v6, v240, sext(v6) dst_sel:DWORD dst_unused:UNUSED_PAD src0_sel:DWORD src1_sel:BYTE_0
	s_add_u32 s14, s20, s12
	v_add_u32_sdwa v8, v3, sext(v6) dst_sel:DWORD dst_unused:UNUSED_PAD src0_sel:DWORD src1_sel:WORD_0
	v_ashrrev_i32_e32 v3, 31, v2
	s_addc_u32 s15, s21, s13
	v_lshlrev_b64 v[6:7], 11, v[2:3]
	v_ashrrev_i32_e32 v9, 31, v8
	v_lshl_add_u64 v[2:3], s[14:15], 0, v[6:7]
	v_lshlrev_b64 v[8:9], 1, v[8:9]
	v_add_u32_e32 v149, 0x2000, v5
	v_lshl_add_u64 v[14:15], v[2:3], 0, v[8:9]
	v_ashrrev_i32_e32 v2, 31, v149
	v_lshrrev_b32_e32 v2, 22, v2
	v_add_u32_e32 v2, v149, v2
	v_ashrrev_i32_e32 v3, 10, v2
	v_mul_i32_i24_e32 v2, 0x400, v3
	v_sub_u32_e32 v2, v149, v2
	v_lshrrev_b32_e32 v10, 4, v2
	v_bitop3_b32 v10, v10, v2, 32 bitop3:0x6c
	v_ashrrev_i32_e32 v11, 31, v10
	v_lshrrev_b32_e32 v11, 26, v11
	v_add_u32_e32 v11, v10, v11
	v_lshlrev_b32_e32 v2, 3, v3
	v_ashrrev_i32_e32 v12, 6, v11
	v_and_b32_e32 v11, 0xc0, v11
	v_and_b32_e32 v2, -16, v2
	v_lshlrev_b32_e32 v3, 5, v3
	v_sub_u32_e32 v10, v10, v11
	v_add_u32_e32 v2, v12, v2
	v_and_b32_e32 v3, 32, v3
	v_ashrrev_i16_sdwa v10, v240, sext(v10) dst_sel:DWORD dst_unused:UNUSED_PAD src0_sel:DWORD src1_sel:BYTE_0
	v_add_u32_sdwa v12, v3, sext(v10) dst_sel:DWORD dst_unused:UNUSED_PAD src0_sel:DWORD src1_sel:WORD_0
	v_ashrrev_i32_e32 v3, 31, v2
	v_lshlrev_b64 v[10:11], 11, v[2:3]
	s_ashr_i32 s11, s10, 31
	v_lshl_add_u64 v[2:3], s[14:15], 0, v[10:11]
	s_lshl_b64 s[14:15], s[10:11], 11
	v_ashrrev_i32_e32 v13, 31, v12
	s_add_u32 s16, s18, s14
	v_lshlrev_b64 v[12:13], 1, v[12:13]
	s_addc_u32 s17, s19, s15
	v_lshl_add_u64 v[16:17], v[2:3], 0, v[12:13]
	v_lshl_add_u64 v[2:3], s[16:17], 0, v[6:7]
	v_lshl_add_u64 v[18:19], v[2:3], 0, v[8:9]
	v_lshl_add_u64 v[2:3], s[16:17], 0, v[10:11]
	s_or_b32 s16, s8, 0x80
	s_ashr_i32 s17, s16, 31
	s_lshl_b64 s[16:17], s[16:17], 11
	s_add_u32 s16, s20, s16
	v_add_u32_e32 v148, 0x10000, v5
	s_addc_u32 s17, s21, s17
	v_readfirstlane_b32 s9, v148
	v_add_u32_e32 v151, 0x12000, v5
	v_lshl_add_u64 v[20:21], v[2:3], 0, v[12:13]
	v_lshl_add_u64 v[2:3], s[16:17], 0, v[6:7]
	s_mov_b32 m0, s9
	v_readfirstlane_b32 s9, v151
	v_lshl_add_u64 v[22:23], v[2:3], 0, v[8:9]
	v_lshl_add_u64 v[2:3], s[16:17], 0, v[10:11]
	s_or_b32 s16, s10, 0x80
	s_waitcnt vmcnt(63) expcnt(7) lgkmcnt(15)
	s_barrier
	global_load_lds_dwordx4 v[14:15], off
	s_mov_b32 m0, s9
	v_readfirstlane_b32 s9, v5
	s_ashr_i32 s17, s16, 31
	global_load_lds_dwordx4 v[16:17], off
	s_mov_b32 m0, s9
	v_readfirstlane_b32 s9, v149
	v_add_u32_e32 v153, 0x14000, v5
	s_lshl_b64 s[16:17], s[16:17], 11
	global_load_lds_dwordx4 v[18:19], off
	s_mov_b32 m0, s9
	v_readfirstlane_b32 s9, v153
	v_add_u32_e32 v154, 0x16000, v5
	s_add_u32 s16, s18, s16
	global_load_lds_dwordx4 v[20:21], off
	s_mov_b32 m0, s9
	v_readfirstlane_b32 s9, v154
	s_addc_u32 s17, s19, s17
	v_add_u32_e32 v155, 0x4000, v5
	global_load_lds_dwordx4 v[22:23], off
	s_nop 0
	v_lshl_add_u64 v[24:25], v[2:3], 0, v[12:13]
	s_mov_b32 m0, s9
	v_lshl_add_u64 v[2:3], s[16:17], 0, v[6:7]
	v_readfirstlane_b32 s9, v155
	v_add_u32_e32 v156, 0x6000, v5
	global_load_lds_dwordx4 v[24:25], off
	v_lshl_add_u64 v[2:3], v[2:3], 0, v[8:9]
	s_mov_b32 m0, s9
	v_lshl_add_u64 v[26:27], s[16:17], 0, v[10:11]
	v_readfirstlane_b32 s9, v156
	global_load_lds_dwordx4 v[2:3], off
	v_lshl_add_u64 v[134:135], v[26:27], 0, v[12:13]
	s_mov_b32 m0, s9
	v_ashrrev_i32_e32 v26, 8, v0
	global_load_lds_dwordx4 v[134:135], off
	v_cmp_eq_u32_e32 vcc, 1, v26
	s_and_saveexec_b64 s[16:17], vcc
	s_cbranch_execz .LBB0_1033
	s_barrier

.LBB0_1714:
	s_waitcnt vmcnt(0)
	global_load_dwordx4 v[30:33], v[156:157], off
	global_load_dwordx4 v[34:37], v[158:159], off
	global_load_dwordx4 v[38:41], v[160:161], off
	global_load_dwordx4 v[42:45], v[164:165], off
	global_load_dwordx4 v[46:49], v[166:167], off
	v_mov_b32_e32 v149, v1
	v_mov_b32_e32 v151, v1
	v_lshl_add_u64 v[156:157], v[156:157], 0, v[0:1]
	v_lshl_add_u64 v[158:159], v[158:159], 0, v[148:149]
	v_lshl_add_u64 v[160:161], v[160:161], 0, v[150:151]
	v_lshl_add_u64 v[164:165], v[164:165], 0, s[44:45]
	v_lshl_add_u64 v[166:167], v[166:167], 0, s[44:45]
	v_cmp_lt_i32_e32 vcc, 0, v3
	s_and_saveexec_b64 s[14:15], vcc
	s_cbranch_execz .LBB0_1730

; __device__ __forceinline__ float max3f(float a, float b, float c) { float r; asm("v_max3_f32 %0, %1, %2, %3" : "=v"(r) : "v"(a), "v"(b), "v"(c)); return r; }
; template <int DQK>
; __device__ __forceinline__ void attn_block(const AttnKV& a, const AttnW& gw, char* smem) {
;     ...
;                 float mxa = max3f(st[qt][0][0], st[qt][0][1], st[qt][0][2]), mxb = max3f(st[qt][0][3], st[qt][1][0], st[qt][1][1]);
;                 mxa = max3f(mxa, st[qt][1][2], st[qt][1][3]);
; #pragma unroll
;                 for (int nt = 2; nt < 8; nt += 2) {
;                     mxb = max3f(mxb, st[qt][nt][0], st[qt][nt][1]); mxa = max3f(mxa, st[qt][nt][2], st[qt][nt][3]);
;                     mxb = max3f(mxb, st[qt][nt + 1][0], st[qt][nt + 1][1]); mxa = max3f(mxa, st[qt][nt + 1][2], st[qt][nt + 1][3]);
;                 }
;                 float mx = fmaxf(mxa, mxb);
;                 mx = fmaxf(mx, __shfl_xor(mx, 16)); mx = fmaxf(mx, __shfl_xor(mx, 32));
;                 const float mnew = fmaxf(m[qt], mx);
;                 const float alpha = __builtin_amdgcn_exp2f(m[qt] - mnew);
;                 m[qt] = mnew;
;                 f32x4 rs4 = {0.f, 0.f, 0.f, 0.f};
;                 const f32x4 negm4 = {-mnew, -mnew, -mnew, -mnew};
; #pragma unroll
;                 for (int nt = 0; nt < 8; ++nt) {
;                     const f32x4 d4 = st[qt][nt] + negm4;
;                     f32x4 e4;
;                     e4[0] = __builtin_amdgcn_exp2f(d4[0]); e4[1] = __builtin_amdgcn_exp2f(d4[1]); e4[2] = __builtin_amdgcn_exp2f(d4[2]); e4[3] = __builtin_amdgcn_exp2f(d4[3]);
;                     st[qt][nt] = e4; rs4 += e4;
;                 }
;                 float rs = (rs4[0] + rs4[1]) + (rs4[2] + rs4[3]);
;                 rs += __shfl_xor(rs, 16); rs += __shfl_xor(rs, 32);
;                 l[qt] = l[qt] * alpha + rs;
;                 if (__builtin_amdgcn_ballot_w64(alpha != 1.0f) != 0ull) {
; #pragma unroll
;                     for (int dt = 0; dt < 4; ++dt) ot[qt][dt] *= alpha;
;                 }
.LBB0_1723:
	s_or_b64 exec, exec, s[16:17]
	s_setprio 0
	v_max3_f32 v149, v114, v115, v116
	v_max3_f32 v151, v117, v118, v119
	v_and_b32_e32 v168, 64, v237
	v_max3_f32 v149, v149, v120, v121
	v_max3_f32 v151, v151, v122, v123
	v_add_u32_e32 v168, 64, v168
	v_max3_f32 v149, v149, v124, v125
	v_max3_f32 v151, v151, v126, v127
	s_nop 0
	v_max3_f32 v149, v149, v128, v129
	v_max3_f32 v151, v151, v130, v131
	s_nop 0
	v_max3_f32 v149, v149, v132, v133
	v_max3_f32 v151, v151, v134, v135
	s_nop 0
	v_max3_f32 v149, v149, v136, v137
	v_max3_f32 v151, v151, v138, v139
	s_nop 0
	v_max3_f32 v149, v149, v140, v141
	v_max3_f32 v151, v151, v142, v143
	s_nop 0
	v_max3_f32 v149, v149, v144, v145
	v_max_f32_e32 v151, v151, v151
	v_max_f32_e32 v149, v149, v149
	v_max_f32_e32 v151, v149, v151
	v_mov_b32_e32 v170, v151
	s_nop 1
	v_permlane16_swap_b32 v151, v170
	v_max_f32_e32 v170, v151, v170
	v_mov_b32_e32 v151, v170
	s_nop 1
	v_permlane32_swap_b32 v170, v151
	v_max3_f32 v168, v186, v170, v151
	v_pk_add_f32 v[116:117], v[116:117], v[168:169] op_sel_hi:[1,0] neg_lo:[0,1] neg_hi:[0,1]
	v_pk_add_f32 v[114:115], v[114:115], v[168:169] op_sel_hi:[1,0] neg_lo:[0,1] neg_hi:[0,1]
	v_exp_f32_e32 v180, v116
	v_exp_f32_e32 v178, v114
	v_exp_f32_e32 v179, v115
	v_exp_f32_e32 v181, v117
	v_pk_add_f32 v[114:115], v[120:121], v[168:169] op_sel_hi:[1,0] neg_lo:[0,1] neg_hi:[0,1]
	v_pk_add_f32 v[116:117], v[118:119], v[168:169] op_sel_hi:[1,0] neg_lo:[0,1] neg_hi:[0,1]
	v_exp_f32_e32 v184, v114
	v_exp_f32_e32 v182, v116
	v_exp_f32_e32 v185, v115
	v_exp_f32_e32 v183, v117
	v_pk_add_f32 v[118:119], v[124:125], v[168:169] op_sel_hi:[1,0] neg_lo:[0,1] neg_hi:[0,1]
	v_pk_add_f32 v[120:121], v[122:123], v[168:169] op_sel_hi:[1,0] neg_lo:[0,1] neg_hi:[0,1]
	v_exp_f32_e32 v172, v118
	v_exp_f32_e32 v170, v120
	v_exp_f32_e32 v171, v121
	v_exp_f32_e32 v173, v119
	v_pk_add_f32 v[118:119], v[128:129], v[168:169] op_sel_hi:[1,0] neg_lo:[0,1] neg_hi:[0,1]
	v_pk_add_f32 v[120:121], v[126:127], v[168:169] op_sel_hi:[1,0] neg_lo:[0,1] neg_hi:[0,1]
	v_exp_f32_e32 v176, v118
	v_exp_f32_e32 v174, v120
	v_exp_f32_e32 v177, v119
	v_exp_f32_e32 v175, v121
	v_pk_add_f32 v[118:119], v[132:133], v[168:169] op_sel_hi:[1,0] neg_lo:[0,1] neg_hi:[0,1]
	v_pk_add_f32 v[120:121], v[130:131], v[168:169] op_sel_hi:[1,0] neg_lo:[0,1] neg_hi:[0,1]
	v_pk_add_f32 v[114:115], v[178:179], 0 op_sel_hi:[1,0]
	v_pk_add_f32 v[116:117], v[180:181], 0 op_sel_hi:[1,0]
	v_exp_f32_e32 v126, v120
	v_exp_f32_e32 v127, v121
	v_exp_f32_e32 v128, v118
	v_exp_f32_e32 v129, v119
	v_pk_add_f32 v[118:119], v[136:137], v[168:169] op_sel_hi:[1,0] neg_lo:[0,1] neg_hi:[0,1]
	v_pk_add_f32 v[120:121], v[134:135], v[168:169] op_sel_hi:[1,0] neg_lo:[0,1] neg_hi:[0,1]
	v_pk_add_f32 v[116:117], v[184:185], v[116:117]
	v_pk_add_f32 v[114:115], v[182:183], v[114:115]
	v_exp_f32_e32 v130, v120
	v_exp_f32_e32 v132, v118
	v_exp_f32_e32 v133, v119
	v_exp_f32_e32 v131, v121
	v_pk_add_f32 v[120:121], v[140:141], v[168:169] op_sel_hi:[1,0] neg_lo:[0,1] neg_hi:[0,1]
	v_pk_add_f32 v[118:119], v[138:139], v[168:169] op_sel_hi:[1,0] neg_lo:[0,1] neg_hi:[0,1]
	v_pk_add_f32 v[114:115], v[170:171], v[114:115]
	v_pk_add_f32 v[116:117], v[172:173], v[116:117]
	v_exp_f32_e32 v118, v118
	v_exp_f32_e32 v119, v119
	v_exp_f32_e32 v120, v120
	v_exp_f32_e32 v121, v121
	v_pk_add_f32 v[124:125], v[144:145], v[168:169] op_sel_hi:[1,0] neg_lo:[0,1] neg_hi:[0,1]
	v_pk_add_f32 v[122:123], v[142:143], v[168:169] op_sel_hi:[1,0] neg_lo:[0,1] neg_hi:[0,1]
	v_pk_add_f32 v[116:117], v[176:177], v[116:117]
	v_pk_add_f32 v[114:115], v[174:175], v[114:115]
	v_exp_f32_e32 v122, v122
	v_exp_f32_e32 v124, v124
	v_exp_f32_e32 v125, v125
	v_exp_f32_e32 v123, v123
	v_pk_add_f32 v[114:115], v[126:127], v[114:115]
	v_pk_add_f32 v[116:117], v[128:129], v[116:117]
	v_pk_add_f32 v[114:115], v[130:131], v[114:115]
	v_pk_add_f32 v[116:117], v[132:133], v[116:117]
	v_pk_add_f32 v[114:115], v[118:119], v[114:115]
	v_pk_add_f32 v[116:117], v[120:121], v[116:117]
	v_pk_add_f32 v[114:115], v[122:123], v[114:115]
	v_pk_add_f32 v[116:117], v[124:125], v[116:117]
	v_add_f32_e32 v114, v114, v115
	v_add_f32_e32 v115, v116, v117
	v_add_f32_e32 v115, v114, v115
	v_mov_b32_e32 v116, v115
	v_sub_f32_e32 v114, v186, v168
	v_exp_f32_e32 v114, v114
	v_permlane16_swap_b32 v115, v116
	v_add_f32_e32 v115, v115, v116
	v_mov_b32_e32 v117, v115
	s_nop 1
	v_permlane32_swap_b32 v115, v117
	v_cmp_neq_f32_e32 vcc, 1.0, v114
	s_cbranch_vccz .LBB0_1725
	v_pk_mul_f32 v[80:81], v[80:81], v[114:115] op_sel_hi:[1,0]
	v_pk_mul_f32 v[78:79], v[78:79], v[114:115] op_sel_hi:[1,0]
	v_pk_mul_f32 v[76:77], v[76:77], v[114:115] op_sel_hi:[1,0]
	v_pk_mul_f32 v[74:75], v[74:75], v[114:115] op_sel_hi:[1,0]
	v_pk_mul_f32 v[72:73], v[72:73], v[114:115] op_sel_hi:[1,0]
	v_pk_mul_f32 v[70:71], v[70:71], v[114:115] op_sel_hi:[1,0]
	v_pk_mul_f32 v[68:69], v[68:69], v[114:115] op_sel_hi:[1,0]
	v_pk_mul_f32 v[66:67], v[66:67], v[114:115] op_sel_hi:[1,0]
; __device__ __forceinline__ float max3f(float a, float b, float c) { float r; asm("v_max3_f32 %0, %1, %2, %3" : "=v"(r) : "v"(a), "v"(b), "v"(c)); return r; }
; template <int DQK>
; __device__ __forceinline__ void attn_block(const AttnKV& a, const AttnW& gw, char* smem) {
;     ...
;                 float mxa = max3f(st[qt][0][0], st[qt][0][1], st[qt][0][2]), mxb = max3f(st[qt][0][3], st[qt][1][0], st[qt][1][1]);
;                 mxa = max3f(mxa, st[qt][1][2], st[qt][1][3]);
; #pragma unroll
;                 for (int nt = 2; nt < 8; nt += 2) {
;                     mxb = max3f(mxb, st[qt][nt][0], st[qt][nt][1]); mxa = max3f(mxa, st[qt][nt][2], st[qt][nt][3]);
;                     mxb = max3f(mxb, st[qt][nt + 1][0], st[qt][nt + 1][1]); mxa = max3f(mxa, st[qt][nt + 1][2], st[qt][nt + 1][3]);
;                 }
;                 float mx = fmaxf(mxa, mxb);
;                 mx = fmaxf(mx, __shfl_xor(mx, 16)); mx = fmaxf(mx, __shfl_xor(mx, 32));
;                 const float mnew = fmaxf(m[qt], mx);
;                 const float alpha = __builtin_amdgcn_exp2f(m[qt] - mnew);
;                 m[qt] = mnew;
;                 f32x4 rs4 = {0.f, 0.f, 0.f, 0.f};
;                 const f32x4 negm4 = {-mnew, -mnew, -mnew, -mnew};
; #pragma unroll
;                 for (int nt = 0; nt < 8; ++nt) {
;                     const f32x4 d4 = st[qt][nt] + negm4;
;                     f32x4 e4;
;                     e4[0] = __builtin_amdgcn_exp2f(d4[0]); e4[1] = __builtin_amdgcn_exp2f(d4[1]); e4[2] = __builtin_amdgcn_exp2f(d4[2]); e4[3] = __builtin_amdgcn_exp2f(d4[3]);
;                     st[qt][nt] = e4; rs4 += e4;
;                 }
;                 float rs = (rs4[0] + rs4[1]) + (rs4[2] + rs4[3]);
;                 rs += __shfl_xor(rs, 16); rs += __shfl_xor(rs, 32);
;                 l[qt] = l[qt] * alpha + rs;
;                 if (__builtin_amdgcn_ballot_w64(alpha != 1.0f) != 0ull) {
; #pragma unroll
;                     for (int dt = 0; dt < 4; ++dt) ot[qt][dt] *= alpha;
;                 }
.LBB0_1725:
	v_max3_f32 v116, v82, v83, v84
	v_max3_f32 v134, v85, v86, v87
	s_nop 0
	v_max3_f32 v116, v116, v88, v89
	v_max3_f32 v134, v134, v90, v91
	s_nop 0
	v_max3_f32 v116, v116, v92, v93
	v_max3_f32 v134, v134, v98, v99
	s_nop 0
	v_max3_f32 v116, v116, v100, v101
	v_max3_f32 v134, v134, v102, v103
	s_nop 0
	v_max3_f32 v116, v116, v104, v105
	v_max3_f32 v134, v134, v94, v95
	s_nop 0
	v_max3_f32 v116, v116, v96, v97
	v_max3_f32 v134, v134, v110, v111
	s_nop 0
	v_max3_f32 v116, v116, v112, v113
	v_max3_f32 v134, v134, v106, v107
	s_nop 0
	v_max3_f32 v116, v116, v108, v109
	v_max_f32_e32 v134, v134, v134
	v_max_f32_e32 v116, v116, v116
	v_max_f32_e32 v116, v116, v134
	v_mov_b32_e32 v134, v116
	s_nop 1
	v_permlane16_swap_b32 v116, v134
	v_max_f32_e32 v116, v116, v134
	v_mov_b32_e32 v134, v116
	s_nop 1
	v_permlane32_swap_b32 v116, v134
	v_max3_f32 v116, v193, v116, v134
	v_pk_add_f32 v[84:85], v[84:85], v[116:117] op_sel_hi:[1,0] neg_lo:[0,1] neg_hi:[0,1]
	v_pk_add_f32 v[82:83], v[82:83], v[116:117] op_sel_hi:[1,0] neg_lo:[0,1] neg_hi:[0,1]
	v_exp_f32_e32 v142, v84
	v_exp_f32_e32 v140, v82
	v_exp_f32_e32 v141, v83
	v_exp_f32_e32 v143, v85
	v_pk_add_f32 v[82:83], v[88:89], v[116:117] op_sel_hi:[1,0] neg_lo:[0,1] neg_hi:[0,1]
	v_pk_add_f32 v[84:85], v[86:87], v[116:117] op_sel_hi:[1,0] neg_lo:[0,1] neg_hi:[0,1]
	v_exp_f32_e32 v186, v82
	v_exp_f32_e32 v187, v83
	v_pk_add_f32 v[86:87], v[92:93], v[116:117] op_sel_hi:[1,0] neg_lo:[0,1] neg_hi:[0,1]
	v_pk_add_f32 v[88:89], v[90:91], v[116:117] op_sel_hi:[1,0] neg_lo:[0,1] neg_hi:[0,1]
	v_exp_f32_e32 v136, v86
	v_exp_f32_e32 v137, v87
	v_pk_add_f32 v[86:87], v[100:101], v[116:117] op_sel_hi:[1,0] neg_lo:[0,1] neg_hi:[0,1]
	v_exp_f32_e32 v144, v84
	v_exp_f32_e32 v138, v86
	v_exp_f32_e32 v139, v87
	v_pk_add_f32 v[86:87], v[104:105], v[116:117] op_sel_hi:[1,0] neg_lo:[0,1] neg_hi:[0,1]
	v_exp_f32_e32 v145, v85
	v_pk_add_f32 v[84:85], v[142:143], 0 op_sel_hi:[1,0]
	v_exp_f32_e32 v134, v88
	v_exp_f32_e32 v135, v89
	v_pk_add_f32 v[88:89], v[98:99], v[116:117] op_sel_hi:[1,0] neg_lo:[0,1] neg_hi:[0,1]
	v_exp_f32_e32 v98, v86
	v_exp_f32_e32 v99, v87
	v_pk_add_f32 v[86:87], v[96:97], v[116:117] op_sel_hi:[1,0] neg_lo:[0,1] neg_hi:[0,1]
	v_pk_add_f32 v[84:85], v[186:187], v[84:85]
	v_exp_f32_e32 v96, v86
	v_exp_f32_e32 v97, v87
	v_pk_add_f32 v[84:85], v[136:137], v[84:85]
	v_exp_f32_e32 v100, v88
	v_exp_f32_e32 v101, v89
	v_pk_add_f32 v[84:85], v[138:139], v[84:85]
	v_pk_add_f32 v[88:89], v[102:103], v[116:117] op_sel_hi:[1,0] neg_lo:[0,1] neg_hi:[0,1]
	v_pk_add_f32 v[82:83], v[140:141], 0 op_sel_hi:[1,0]
	v_exp_f32_e32 v92, v88
	v_exp_f32_e32 v93, v89
	v_pk_add_f32 v[88:89], v[94:95], v[116:117] op_sel_hi:[1,0] neg_lo:[0,1] neg_hi:[0,1]
	v_pk_add_f32 v[84:85], v[98:99], v[84:85]
	v_pk_add_f32 v[82:83], v[144:145], v[82:83]
	v_exp_f32_e32 v94, v88
	v_exp_f32_e32 v95, v89
	v_pk_add_f32 v[102:103], v[96:97], v[84:85]
	v_pk_add_f32 v[86:87], v[112:113], v[116:117] op_sel_hi:[1,0] neg_lo:[0,1] neg_hi:[0,1]
	v_pk_add_f32 v[84:85], v[110:111], v[116:117] op_sel_hi:[1,0] neg_lo:[0,1] neg_hi:[0,1]
	v_pk_add_f32 v[82:83], v[134:135], v[82:83]
	v_exp_f32_e32 v84, v84
	v_exp_f32_e32 v85, v85
	v_exp_f32_e32 v86, v86
	v_exp_f32_e32 v87, v87
	v_pk_add_f32 v[90:91], v[108:109], v[116:117] op_sel_hi:[1,0] neg_lo:[0,1] neg_hi:[0,1]
	v_pk_add_f32 v[88:89], v[106:107], v[116:117] op_sel_hi:[1,0] neg_lo:[0,1] neg_hi:[0,1]
	v_pk_add_f32 v[82:83], v[100:101], v[82:83]
	v_exp_f32_e32 v88, v88
	v_exp_f32_e32 v90, v90
	v_exp_f32_e32 v91, v91
	v_exp_f32_e32 v89, v89
	v_pk_add_f32 v[82:83], v[92:93], v[82:83]
	v_pk_add_f32 v[102:103], v[86:87], v[102:103]
	v_pk_add_f32 v[82:83], v[94:95], v[82:83]
	v_pk_add_f32 v[102:103], v[90:91], v[102:103]
	v_pk_add_f32 v[82:83], v[84:85], v[82:83]
	s_nop 0
	v_pk_add_f32 v[82:83], v[88:89], v[82:83]
	s_nop 0
	v_add_f32_e32 v82, v82, v83
	v_add_f32_e32 v83, v102, v103
	v_add_f32_e32 v83, v82, v83
	v_mov_b32_e32 v102, v83
	v_sub_f32_e32 v82, v193, v116
	v_exp_f32_e32 v82, v82
	v_permlane16_swap_b32 v83, v102
	v_add_f32_e32 v83, v83, v102
	v_mov_b32_e32 v102, v83
	s_nop 1
	v_permlane32_swap_b32 v83, v102
	v_cmp_neq_f32_e32 vcc, 1.0, v82
	s_cbranch_vccz .LBB0_1727
	v_pk_mul_f32 v[64:65], v[64:65], v[82:83] op_sel_hi:[1,0]
	v_pk_mul_f32 v[62:63], v[62:63], v[82:83] op_sel_hi:[1,0]
	v_pk_mul_f32 v[60:61], v[60:61], v[82:83] op_sel_hi:[1,0]
	v_pk_mul_f32 v[58:59], v[58:59], v[82:83] op_sel_hi:[1,0]
	v_pk_mul_f32 v[56:57], v[56:57], v[82:83] op_sel_hi:[1,0]
	v_pk_mul_f32 v[54:55], v[54:55], v[82:83] op_sel_hi:[1,0]
	v_pk_mul_f32 v[52:53], v[52:53], v[82:83] op_sel_hi:[1,0]
	v_pk_mul_f32 v[50:51], v[50:51], v[82:83] op_sel_hi:[1,0]

; #define STAGE(P, BASE, LD, br, kt) do { const long _g = (long)(br) * (LD) + (long)(kt) * 64; \
;     _Pragma("unroll") for (int _i = 0; _i < 2; ++_i) { const int _b = tid * 16 + _i * 8192; int _r, _c; stage_rc(_b, _r, _c); \
;       __builtin_amdgcn_global_load_lds((const G_AS1 unsigned*)((BASE) + _g + (long)_r * (LD) + _c), \
;         (LAS unsigned*)((char*)(P) + _b), 16, 0, 0); } } while (0)
; #define BAR __builtin_amdgcn_s_barrier()
; __device__ __forceinline__ void gemm256(const bf16_t* __restrict__ A, long lda, const bf16_t* __restrict__ Bt, long ldb, int K,
;                                         int brow, int bcol, char* smem, f32x4 (&acc)[2][2][4][2]) {
;     ...
;     const int wid = tid >> 6, lane = tid & 63, wr = wid >> 2, wc = wid & 3, fr = lane & 15, fq = lane >> 4;
; #pragma unroll
;     for (int ai = 0; ai < 2; ++ai)
; #pragma unroll
;         for (int bj = 0; bj < 2; ++bj)
; #pragma unroll
;             for (int m = 0; m < 4; ++m)
; #pragma unroll
;                 for (int n = 0; n < 2; ++n) acc[ai][bj][m][n] = (f32x4){0.f, 0.f, 0.f, 0.f};
;     bf16x8 At[4][2], B0[2][2], B1[2][2];
;     const int nt = K / 64;
;     __syncthreads();
;     STAGE(SB(0, 0), Bt, ldb, bcol, 0); STAGE(SA(0, 0), A, lda, brow, 0);
;     STAGE(SB(0, 1), Bt, ldb, bcol + 128, 0); STAGE(SA(0, 1), A, lda, brow + 128, 0);
;     if (wr == 1) BAR;
.LBB0_1865:
	s_and_b64 vcc, exec, s[6:7]
	s_cbranch_vccz .LBB0_1858
	s_ashr_i32 s6, s1, 31
	s_lshr_b32 s6, s6, 29
	s_add_i32 s6, s1, s6
	s_ashr_i32 s7, s6, 3
	s_and_b32 s6, s6, -8
	s_sub_i32 s6, s1, s6
	s_cmp_lt_i32 s6, 0
	s_movk_i32 s8, 0x43
	s_cselect_b32 s8, s8, 0x42
	s_mul_i32 s6, s6, s8
	s_add_i32 s6, s6, s7
	s_ashr_i32 s7, s6, 31
	s_lshr_b32 s7, s7, 28
	s_add_i32 s8, s6, s7
	s_and_b32 s7, s8, 0xfff0
	s_sub_i32 s9, s6, s7
	s_bfe_i32 s6, s9, 0x80000
	s_bfe_u32 s6, s6, 0x2000d
	v_mov_b32_e32 v0, v236
	s_add_i32 s10, s9, s6
	s_load_dwordx2 s[6:7], s[4:5], 0x130
	s_bfe_i32 s11, s10, 0x80000
	v_ashrrev_i32_e32 v2, 31, v0
	v_lshrrev_b32_e32 v2, 26, v2
	v_add_u32_e32 v2, v0, v2
	v_ashrrev_i32_e32 v3, 6, v2
	v_bfe_i32 v2, v0, 27, 1
	v_lshlrev_b32_e32 v5, 4, v0
	v_lshrrev_b32_e32 v2, 22, v2
	s_and_b32 s10, s10, 0xfc
	v_add_u32_e32 v2, v5, v2
	s_sub_i32 s9, s9, s10
	v_and_b32_e32 v2, 0xfffffc00, v2
	s_waitcnt lgkmcnt(0)
	s_add_u32 s18, s6, 0x346c000
	v_sub_u32_e32 v2, v5, v2
	s_addc_u32 s19, s7, 0
	v_lshrrev_b32_e32 v6, 4, v2
	s_add_u32 s20, s6, 0x2b8c000
	v_bitop3_b32 v6, v6, v2, 32 bitop3:0x6c
	v_ashrrev_i32_e32 v2, 31, v2
	s_sext_i32_i8 s9, s9
	s_addc_u32 s21, s7, 0
	s_lshl_b32 s8, s8, 6
	v_lshrrev_b32_e32 v2, 26, v2
	s_sext_i32_i16 s11, s11
	s_and_b32 s8, s8, 0xfffffc00
	s_lshl_b32 s9, s9, 8
	v_lshlrev_b32_e32 v7, 3, v3
	v_add_u32_e32 v2, v6, v2
	s_add_i32 s10, s9, s8
	s_lshl_b32 s8, s11, 6
	v_and_b32_e32 v7, -16, v7
	v_ashrrev_i32_e32 v8, 6, v2
	s_and_b32 s8, s8, 0xffffff00
	v_add_u32_e32 v2, v8, v7
	v_mul_i32_i24_e32 v7, 64, v8
	s_ashr_i32 s9, s8, 31
	v_lshlrev_b32_e32 v3, 5, v3
	v_sub_u32_e32 v6, v6, v7
	s_lshl_b64 s[12:13], s[8:9], 11
	v_and_b32_e32 v3, 32, v3
	v_ashrrev_i16_sdwa v6, v240, sext(v6) dst_sel:DWORD dst_unused:UNUSED_PAD src0_sel:DWORD src1_sel:BYTE_0
	s_add_u32 s14, s20, s12
	v_add_u32_sdwa v8, v3, sext(v6) dst_sel:DWORD dst_unused:UNUSED_PAD src0_sel:DWORD src1_sel:WORD_0
	v_ashrrev_i32_e32 v3, 31, v2
	s_addc_u32 s15, s21, s13
	v_lshlrev_b64 v[6:7], 11, v[2:3]
	v_ashrrev_i32_e32 v9, 31, v8
	v_lshl_add_u64 v[2:3], s[14:15], 0, v[6:7]
	v_lshlrev_b64 v[8:9], 1, v[8:9]
	v_add_u32_e32 v149, 0x2000, v5
	v_lshl_add_u64 v[14:15], v[2:3], 0, v[8:9]
	v_ashrrev_i32_e32 v2, 31, v149
	v_lshrrev_b32_e32 v2, 22, v2
	v_add_u32_e32 v2, v149, v2
	v_ashrrev_i32_e32 v3, 10, v2
	v_mul_i32_i24_e32 v2, 0x400, v3
	v_sub_u32_e32 v2, v149, v2
	v_lshrrev_b32_e32 v10, 4, v2
	v_bitop3_b32 v10, v10, v2, 32 bitop3:0x6c
	v_ashrrev_i32_e32 v11, 31, v10
	v_lshrrev_b32_e32 v11, 26, v11
	v_add_u32_e32 v11, v10, v11
	v_lshlrev_b32_e32 v2, 3, v3
	v_ashrrev_i32_e32 v12, 6, v11
	v_and_b32_e32 v11, 0xc0, v11
	v_and_b32_e32 v2, -16, v2
	v_lshlrev_b32_e32 v3, 5, v3
	v_sub_u32_e32 v10, v10, v11
	v_add_u32_e32 v2, v12, v2
	v_and_b32_e32 v3, 32, v3
	v_ashrrev_i16_sdwa v10, v240, sext(v10) dst_sel:DWORD dst_unused:UNUSED_PAD src0_sel:DWORD src1_sel:BYTE_0
	v_add_u32_sdwa v12, v3, sext(v10) dst_sel:DWORD dst_unused:UNUSED_PAD src0_sel:DWORD src1_sel:WORD_0
	v_ashrrev_i32_e32 v3, 31, v2
	v_lshlrev_b64 v[10:11], 11, v[2:3]
	s_ashr_i32 s11, s10, 31
	v_lshl_add_u64 v[2:3], s[14:15], 0, v[10:11]
	s_lshl_b64 s[14:15], s[10:11], 11
	v_ashrrev_i32_e32 v13, 31, v12
	s_add_u32 s16, s18, s14
	v_lshlrev_b64 v[12:13], 1, v[12:13]
	s_addc_u32 s17, s19, s15
	v_lshl_add_u64 v[16:17], v[2:3], 0, v[12:13]
	v_lshl_add_u64 v[2:3], s[16:17], 0, v[6:7]
	v_lshl_add_u64 v[18:19], v[2:3], 0, v[8:9]
	v_lshl_add_u64 v[2:3], s[16:17], 0, v[10:11]
	s_or_b32 s16, s8, 0x80
	s_ashr_i32 s17, s16, 31
	s_lshl_b64 s[16:17], s[16:17], 11
	s_add_u32 s16, s20, s16
	v_add_u32_e32 v148, 0x10000, v5
	s_addc_u32 s17, s21, s17
	v_readfirstlane_b32 s9, v148
	v_add_u32_e32 v151, 0x12000, v5
	v_lshl_add_u64 v[20:21], v[2:3], 0, v[12:13]
	v_lshl_add_u64 v[2:3], s[16:17], 0, v[6:7]
	s_mov_b32 m0, s9
	v_readfirstlane_b32 s9, v151
	v_lshl_add_u64 v[22:23], v[2:3], 0, v[8:9]
	v_lshl_add_u64 v[2:3], s[16:17], 0, v[10:11]
	s_or_b32 s16, s10, 0x80
	s_waitcnt vmcnt(63) expcnt(7) lgkmcnt(15)
	s_barrier
	global_load_lds_dwordx4 v[14:15], off
	s_mov_b32 m0, s9
	v_readfirstlane_b32 s9, v5
	s_ashr_i32 s17, s16, 31
	global_load_lds_dwordx4 v[16:17], off
	s_mov_b32 m0, s9
	v_readfirstlane_b32 s9, v149
	v_add_u32_e32 v153, 0x14000, v5
	s_lshl_b64 s[16:17], s[16:17], 11
	global_load_lds_dwordx4 v[18:19], off
	s_mov_b32 m0, s9
	v_readfirstlane_b32 s9, v153
	v_add_u32_e32 v154, 0x16000, v5
	s_add_u32 s16, s18, s16
	global_load_lds_dwordx4 v[20:21], off
	s_mov_b32 m0, s9
	v_readfirstlane_b32 s9, v154
	s_addc_u32 s17, s19, s17
	v_add_u32_e32 v155, 0x4000, v5
	global_load_lds_dwordx4 v[22:23], off
	s_nop 0
	v_lshl_add_u64 v[24:25], v[2:3], 0, v[12:13]
	s_mov_b32 m0, s9
	v_lshl_add_u64 v[2:3], s[16:17], 0, v[6:7]
	v_readfirstlane_b32 s9, v155
	v_add_u32_e32 v156, 0x6000, v5
	global_load_lds_dwordx4 v[24:25], off
	v_lshl_add_u64 v[2:3], v[2:3], 0, v[8:9]
	s_mov_b32 m0, s9
	v_lshl_add_u64 v[26:27], s[16:17], 0, v[10:11]
	v_readfirstlane_b32 s9, v156
	global_load_lds_dwordx4 v[2:3], off
	v_lshl_add_u64 v[134:135], v[26:27], 0, v[12:13]
	s_mov_b32 m0, s9
	v_ashrrev_i32_e32 v26, 8, v0
	global_load_lds_dwordx4 v[134:135], off
	v_cmp_eq_u32_e32 vcc, 1, v26
	s_and_saveexec_b64 s[16:17], vcc
	s_cbranch_execz .LBB0_1868
	s_barrier
